# GEMM1 epilogue fast path: branch-free cvt_pk_bf16 + 2-byte stores for non-edge, non-KV tiles
# baseline (speedup 1.0000x reference)
.Lepi1_0_join:
	s_add_i32 s2, s2, s3
	s_add_i32 s29, s29, s30
	s_xor_b64 s[12:13], s[12:13], s[14:15]
	s_cmpk_gt_i32 s2, 0xdb
	s_cbranch_scc1 .LBB0_467

.LBB0_206:
	s_mul_i32 s8, s6, 0x6000
	s_waitcnt vmcnt(6)
	s_add_i32 s10, s27, s8
	s_mul_i32 s98, s7, 0x6000
	v_lshl_add_u64 v[200:201], v[140:141], 0, s[0:1]
	v_lshl_add_u64 v[202:203], v[138:139], 0, s[0:1]
	s_add_i32 s99, s10, s28
	s_waitcnt lgkmcnt(0)
	s_barrier
	v_add_u32_e32 v182, s98, v142
	v_add_u32_e32 v183, s98, v144
	ds_read_b128 v[166:169], v183
	ds_read_b128 v[150:153], v182
	ds_read_b128 v[170:173], v183 offset:1024
	ds_read_b128 v[174:177], v183 offset:2048
	ds_read_b128 v[178:181], v183 offset:3072
	ds_read_b128 v[154:157], v182 offset:1024
	ds_read_b128 v[158:161], v182 offset:2048
	ds_read_b128 v[162:165], v182 offset:3072
	ds_read_b128 v[184:187], v182 offset:4096
	ds_read_b128 v[188:191], v182 offset:5120
	ds_read_b128 v[192:195], v182 offset:6144
	ds_read_b128 v[196:199], v182 offset:7168
	v_lshl_add_u64 v[204:205], v[200:201], 0, s[20:21]
	s_mov_b32 m0, s10
	s_waitcnt lgkmcnt(10)
	v_mfma_f32_16x16x32_bf16 v[84:87], v[150:153], v[166:169], v[84:87]
	global_load_lds_dwordx4 v[204:205], off
	s_waitcnt lgkmcnt(9)
	v_mfma_f32_16x16x32_bf16 v[76:79], v[150:153], v[170:173], v[76:79]
	v_lshl_add_u64 v[204:205], v[200:201], 0, s[22:23]
	s_add_i32 m0, s10, 0x400
	s_waitcnt lgkmcnt(8)
	v_mfma_f32_16x16x32_bf16 v[68:71], v[150:153], v[174:177], v[68:71]
	global_load_lds_dwordx4 v[204:205], off
	s_waitcnt lgkmcnt(7)
	v_mfma_f32_16x16x32_bf16 v[60:63], v[150:153], v[178:181], v[60:63]
	s_mov_b64 s[100:101], 0x10080
	v_lshl_add_u64 v[204:205], v[200:201], 0, s[100:101]
	s_add_i32 m0, s10, 0x800
	s_waitcnt lgkmcnt(6)
	v_mfma_f32_16x16x32_bf16 v[52:55], v[154:157], v[166:169], v[52:55]
	global_load_lds_dwordx4 v[204:205], off
	v_mfma_f32_16x16x32_bf16 v[44:47], v[154:157], v[170:173], v[44:47]
	v_mfma_f32_16x16x32_bf16 v[36:39], v[154:157], v[174:177], v[36:39]
	s_mov_b64 s[100:101], 0x18080
	v_lshl_add_u64 v[204:205], v[200:201], 0, s[100:101]
	s_add_i32 m0, s10, 0xc00
	v_mfma_f32_16x16x32_bf16 v[32:35], v[154:157], v[178:181], v[32:35]
	global_load_lds_dwordx4 v[204:205], off
	s_waitcnt lgkmcnt(5)
	v_mfma_f32_16x16x32_bf16 v[28:31], v[158:161], v[166:169], v[28:31]
	v_lshl_add_u64 v[204:205], v[202:203], 0, s[20:21]
	s_add_i32 m0, s99, 0x4000
	v_mfma_f32_16x16x32_bf16 v[24:27], v[158:161], v[170:173], v[24:27]
	global_load_lds_dwordx4 v[204:205], off
	v_mfma_f32_16x16x32_bf16 v[20:23], v[158:161], v[174:177], v[20:23]
	v_lshl_add_u64 v[204:205], v[202:203], 0, s[22:23]
	s_add_i32 m0, s99, 0x4400
	v_mfma_f32_16x16x32_bf16 v[16:19], v[158:161], v[178:181], v[16:19]
	global_load_lds_dwordx4 v[204:205], off
	s_waitcnt lgkmcnt(4)
	v_mfma_f32_16x16x32_bf16 v[12:15], v[162:165], v[166:169], v[12:15]
	v_mfma_f32_16x16x32_bf16 v[8:11], v[162:165], v[170:173], v[8:11]
	v_mfma_f32_16x16x32_bf16 v[4:7], v[162:165], v[174:177], v[4:7]
	v_mfma_f32_16x16x32_bf16 v[0:3], v[162:165], v[178:181], v[0:3]
	s_waitcnt lgkmcnt(3)
	v_mfma_f32_16x16x32_bf16 v[124:127], v[184:187], v[166:169], v[124:127]
	v_mfma_f32_16x16x32_bf16 v[120:123], v[184:187], v[170:173], v[120:123]
	v_mfma_f32_16x16x32_bf16 v[116:119], v[184:187], v[174:177], v[116:119]
	v_mfma_f32_16x16x32_bf16 v[112:115], v[184:187], v[178:181], v[112:115]
	s_waitcnt lgkmcnt(2)
	v_mfma_f32_16x16x32_bf16 v[108:111], v[188:191], v[166:169], v[108:111]
	v_mfma_f32_16x16x32_bf16 v[104:107], v[188:191], v[170:173], v[104:107]
	v_mfma_f32_16x16x32_bf16 v[100:103], v[188:191], v[174:177], v[100:103]
	v_mfma_f32_16x16x32_bf16 v[96:99], v[188:191], v[178:181], v[96:99]
	s_waitcnt lgkmcnt(1)
	v_mfma_f32_16x16x32_bf16 v[92:95], v[192:195], v[166:169], v[92:95]
	v_mfma_f32_16x16x32_bf16 v[88:91], v[192:195], v[170:173], v[88:91]
	v_mfma_f32_16x16x32_bf16 v[80:83], v[192:195], v[174:177], v[80:83]
	v_mfma_f32_16x16x32_bf16 v[72:75], v[192:195], v[178:181], v[72:75]
	s_waitcnt lgkmcnt(0)
	v_mfma_f32_16x16x32_bf16 v[64:67], v[196:199], v[166:169], v[64:67]
	v_mfma_f32_16x16x32_bf16 v[56:59], v[196:199], v[170:173], v[56:59]
	v_mfma_f32_16x16x32_bf16 v[48:51], v[196:199], v[174:177], v[48:51]
	v_mfma_f32_16x16x32_bf16 v[40:43], v[196:199], v[178:181], v[40:43]
	s_add_i32 s8, s7, 1
	s_cmp_lg_u32 s7, 2
	s_cselect_b32 s7, s8, 0
	s_add_i32 s8, s6, 1
	s_cmp_lg_u32 s6, 2
	s_cselect_b32 s6, s8, 0
	s_add_u32 s0, s0, 64
	s_addc_u32 s1, s1, 0
	s_cmpk_eq_i32 s0, 0x780
	s_cbranch_scc0 .LBB0_206
	s_waitcnt vmcnt(6)
	s_waitcnt lgkmcnt(0)
	s_barrier
	ds_read_b128 v[138:141], v142
	ds_read_b128 v[150:153], v142 offset:1024
	ds_read_b128 v[154:157], v142 offset:2048
	ds_read_b128 v[158:161], v142 offset:3072
	ds_read_b128 v[162:165], v144
	ds_read_b128 v[166:169], v144 offset:1024
	ds_read_b128 v[170:173], v144 offset:2048
	ds_read_b128 v[174:177], v144 offset:3072
	s_waitcnt lgkmcnt(0)
	s_nop 0
	v_mfma_f32_16x16x32_bf16 v[84:87], v[138:141], v[162:165], v[84:87]
	v_mfma_f32_16x16x32_bf16 v[76:79], v[138:141], v[166:169], v[76:79]
	v_mfma_f32_16x16x32_bf16 v[68:71], v[138:141], v[170:173], v[68:71]
	v_mfma_f32_16x16x32_bf16 v[60:63], v[138:141], v[174:177], v[60:63]
	v_mfma_f32_16x16x32_bf16 v[52:55], v[150:153], v[162:165], v[52:55]
	v_mfma_f32_16x16x32_bf16 v[44:47], v[150:153], v[166:169], v[44:47]
	v_mfma_f32_16x16x32_bf16 v[36:39], v[150:153], v[170:173], v[36:39]
	v_mfma_f32_16x16x32_bf16 v[32:35], v[150:153], v[174:177], v[32:35]
	v_mfma_f32_16x16x32_bf16 v[28:31], v[154:157], v[162:165], v[28:31]
	v_mfma_f32_16x16x32_bf16 v[24:27], v[154:157], v[166:169], v[24:27]
	v_mfma_f32_16x16x32_bf16 v[20:23], v[154:157], v[170:173], v[20:23]
	v_mfma_f32_16x16x32_bf16 v[16:19], v[154:157], v[174:177], v[16:19]
	v_mfma_f32_16x16x32_bf16 v[12:15], v[158:161], v[162:165], v[12:15]
	v_mfma_f32_16x16x32_bf16 v[8:11], v[158:161], v[166:169], v[8:11]
	v_mfma_f32_16x16x32_bf16 v[4:7], v[158:161], v[170:173], v[4:7]
	v_mfma_f32_16x16x32_bf16 v[0:3], v[158:161], v[174:177], v[0:3]
	ds_read_b128 v[138:141], v142 offset:4096
	ds_read_b128 v[150:153], v142 offset:5120
	ds_read_b128 v[154:157], v142 offset:6144
	ds_read_b128 v[158:161], v142 offset:7168
	s_waitcnt lgkmcnt(0)
	s_nop 0
	v_mfma_f32_16x16x32_bf16 v[178:181], v[138:141], v[162:165], v[124:127]
	v_mfma_f32_16x16x32_bf16 v[182:185], v[138:141], v[166:169], v[120:123]
	v_mfma_f32_16x16x32_bf16 v[186:189], v[138:141], v[170:173], v[116:119]
	v_mfma_f32_16x16x32_bf16 v[138:141], v[138:141], v[174:177], v[112:115]
	v_mfma_f32_16x16x32_bf16 v[190:193], v[150:153], v[162:165], v[108:111]
	v_mfma_f32_16x16x32_bf16 v[194:197], v[150:153], v[166:169], v[104:107]
	v_mfma_f32_16x16x32_bf16 v[198:201], v[150:153], v[170:173], v[100:103]
	v_mfma_f32_16x16x32_bf16 v[150:153], v[150:153], v[174:177], v[96:99]
	v_mfma_f32_16x16x32_bf16 v[202:205], v[154:157], v[162:165], v[92:95]
	v_mfma_f32_16x16x32_bf16 v[206:209], v[154:157], v[166:169], v[88:91]
	v_mfma_f32_16x16x32_bf16 v[210:213], v[154:157], v[170:173], v[80:83]
	v_mfma_f32_16x16x32_bf16 v[154:157], v[154:157], v[174:177], v[72:75]
	v_mfma_f32_16x16x32_bf16 v[162:165], v[158:161], v[162:165], v[64:67]
	v_mfma_f32_16x16x32_bf16 v[166:169], v[158:161], v[166:169], v[56:59]
	v_mfma_f32_16x16x32_bf16 v[170:173], v[158:161], v[170:173], v[48:51]
	v_mfma_f32_16x16x32_bf16 v[158:161], v[158:161], v[174:177], v[40:43]
	s_waitcnt vmcnt(0)
	s_waitcnt lgkmcnt(0)
	s_barrier
	ds_read_b128 v[40:43], v148
	ds_read_b128 v[48:51], v148 offset:1024
	ds_read_b128 v[56:59], v148 offset:2048
	ds_read_b128 v[174:177], v148 offset:3072
	ds_read_b128 v[214:217], v149
	ds_read_b128 v[218:221], v149 offset:1024
	ds_read_b128 v[222:225], v149 offset:2048
	ds_read_b128 v[228:231], v149 offset:3072
	s_waitcnt lgkmcnt(0)
	s_nop 0
	v_mfma_f32_16x16x32_bf16 v[116:119], v[40:43], v[218:221], v[76:79]
	v_mfma_f32_16x16x32_bf16 v[120:123], v[40:43], v[222:225], v[68:71]
	v_mfma_f32_16x16x32_bf16 v[64:67], v[174:177], v[214:217], v[12:15]
	v_mfma_f32_16x16x32_bf16 v[68:71], v[174:177], v[218:221], v[8:11]
	v_mfma_f32_16x16x32_bf16 v[72:75], v[174:177], v[222:225], v[4:7]
	v_mfma_f32_16x16x32_bf16 v[76:79], v[174:177], v[228:231], v[0:3]
	ds_read_b128 v[0:3], v148 offset:4096
	ds_read_b128 v[4:7], v148 offset:5120
	ds_read_b128 v[8:11], v148 offset:6144
	ds_read_b128 v[12:15], v148 offset:7168
	s_waitcnt lgkmcnt(0)
	v_mfma_f32_16x16x32_bf16 v[112:115], v[40:43], v[214:217], v[84:87]
	v_mfma_f32_16x16x32_bf16 v[124:127], v[40:43], v[228:231], v[60:63]
	v_mfma_f32_16x16x32_bf16 v[96:99], v[48:51], v[214:217], v[52:55]
	v_mfma_f32_16x16x32_bf16 v[100:103], v[48:51], v[218:221], v[44:47]
	v_mfma_f32_16x16x32_bf16 v[104:107], v[48:51], v[222:225], v[36:39]
	v_mfma_f32_16x16x32_bf16 v[108:111], v[48:51], v[228:231], v[32:35]
	v_mfma_f32_16x16x32_bf16 v[80:83], v[56:59], v[214:217], v[28:31]
	v_mfma_f32_16x16x32_bf16 v[84:87], v[56:59], v[218:221], v[24:27]
	v_mfma_f32_16x16x32_bf16 v[88:91], v[56:59], v[222:225], v[20:23]
	v_mfma_f32_16x16x32_bf16 v[92:95], v[56:59], v[228:231], v[16:19]
	v_mfma_f32_16x16x32_bf16 v[48:51], v[0:3], v[214:217], v[178:181]
	v_mfma_f32_16x16x32_bf16 v[52:55], v[0:3], v[218:221], v[182:185]
	v_mfma_f32_16x16x32_bf16 v[56:59], v[0:3], v[222:225], v[186:189]
	v_mfma_f32_16x16x32_bf16 v[60:63], v[0:3], v[228:231], v[138:141]
	v_mfma_f32_16x16x32_bf16 v[32:35], v[4:7], v[214:217], v[190:193]
	v_mfma_f32_16x16x32_bf16 v[36:39], v[4:7], v[218:221], v[194:197]
	v_mfma_f32_16x16x32_bf16 v[40:43], v[4:7], v[222:225], v[198:201]
	v_mfma_f32_16x16x32_bf16 v[44:47], v[4:7], v[228:231], v[150:153]
	v_mfma_f32_16x16x32_bf16 v[16:19], v[8:11], v[214:217], v[202:205]
	v_mfma_f32_16x16x32_bf16 v[20:23], v[8:11], v[218:221], v[206:209]
	v_mfma_f32_16x16x32_bf16 v[24:27], v[8:11], v[222:225], v[210:213]
	v_mfma_f32_16x16x32_bf16 v[28:31], v[8:11], v[228:231], v[154:157]
	v_mfma_f32_16x16x32_bf16 v[0:3], v[12:15], v[214:217], v[162:165]
	v_mfma_f32_16x16x32_bf16 v[4:7], v[12:15], v[218:221], v[166:169]
	v_mfma_f32_16x16x32_bf16 v[8:11], v[12:15], v[222:225], v[170:173]
	v_mfma_f32_16x16x32_bf16 v[12:15], v[12:15], v[228:231], v[158:161]
	v_add_u32_e32 v150, s4, v129
	v_or_b32_e32 v151, v150, v147
	v_or_b32_e32 v138, s5, v143
	v_mov_b32_e32 v153, v151
	v_mov_b64_e32 v[140:141], s[94:95]
	s_waitcnt lgkmcnt(0)
	s_barrier
	s_cmp_gt_u32 s5, 0xa00
	s_cbranch_scc1 .Lepi1_0_slow
	s_cmp_lt_u32 s4, 0x1000
	s_cbranch_scc0 .Lepi1_0_fast
	s_cmp_eq_u32 s5, 0x180
	s_cbranch_scc1 .Lepi1_0_slow
	s_cmp_eq_u32 s5, 0x200
	s_cbranch_scc1 .Lepi1_0_slow
.Lepi1_0_fast:
	v_add_u32_e32 v154, s4, v129
	v_or_b32_e32 v154, v154, v147
	v_or_b32_e32 v152, s5, v143
	v_mov_b32_e32 v153, 0
	v_mov_b64_e32 v[150:151], s[94:95]
	v_mad_i64_i32 v[150:151], vcc, v154, s43, v[150:151]
	v_lshl_add_u64 v[150:151], v[152:153], 1, v[150:151]
	v_lshl_add_u64 v[150:151], v[150:151], 0, v[130:131]
	s_mov_b64 s[100:101], 0x1520
	s_mov_b64 s[98:99], 0x112a0
	v_cvt_pk_bf16_f32 v156, v112, v116
	v_cvt_pk_bf16_f32 v157, v120, v124
	global_store_short v[150:151], v156, off
	global_store_short_d16_hi v[150:151], v156, off offset:32
	global_store_short v[150:151], v157, off offset:64
	global_store_short_d16_hi v[150:151], v157, off offset:96
	v_lshl_add_u64 v[150:151], v[150:151], 0, s[100:101]
	v_cvt_pk_bf16_f32 v158, v113, v117
	v_cvt_pk_bf16_f32 v159, v121, v125
	global_store_short v[150:151], v158, off
	global_store_short_d16_hi v[150:151], v158, off offset:32
	global_store_short v[150:151], v159, off offset:64
	global_store_short_d16_hi v[150:151], v159, off offset:96
	v_lshl_add_u64 v[150:151], v[150:151], 0, s[100:101]
	v_cvt_pk_bf16_f32 v156, v114, v118
	v_cvt_pk_bf16_f32 v157, v122, v126
	global_store_short v[150:151], v156, off
	global_store_short_d16_hi v[150:151], v156, off offset:32
	global_store_short v[150:151], v157, off offset:64
	global_store_short_d16_hi v[150:151], v157, off offset:96
	v_lshl_add_u64 v[150:151], v[150:151], 0, s[100:101]
	v_cvt_pk_bf16_f32 v158, v115, v119
	v_cvt_pk_bf16_f32 v159, v123, v127
	global_store_short v[150:151], v158, off
	global_store_short_d16_hi v[150:151], v158, off offset:32
	global_store_short v[150:151], v159, off offset:64
	global_store_short_d16_hi v[150:151], v159, off offset:96
	v_lshl_add_u64 v[150:151], v[150:151], 0, s[98:99]
	v_cvt_pk_bf16_f32 v156, v96, v100
	v_cvt_pk_bf16_f32 v157, v104, v108
	global_store_short v[150:151], v156, off
	global_store_short_d16_hi v[150:151], v156, off offset:32
	global_store_short v[150:151], v157, off offset:64
	global_store_short_d16_hi v[150:151], v157, off offset:96
	v_lshl_add_u64 v[150:151], v[150:151], 0, s[100:101]
	v_cvt_pk_bf16_f32 v158, v97, v101
	v_cvt_pk_bf16_f32 v159, v105, v109
	global_store_short v[150:151], v158, off
	global_store_short_d16_hi v[150:151], v158, off offset:32
	global_store_short v[150:151], v159, off offset:64
	global_store_short_d16_hi v[150:151], v159, off offset:96
	v_lshl_add_u64 v[150:151], v[150:151], 0, s[100:101]
	v_cvt_pk_bf16_f32 v156, v98, v102
	v_cvt_pk_bf16_f32 v157, v106, v110
	global_store_short v[150:151], v156, off
	global_store_short_d16_hi v[150:151], v156, off offset:32
	global_store_short v[150:151], v157, off offset:64
	global_store_short_d16_hi v[150:151], v157, off offset:96
	v_lshl_add_u64 v[150:151], v[150:151], 0, s[100:101]
	v_cvt_pk_bf16_f32 v158, v99, v103
	v_cvt_pk_bf16_f32 v159, v107, v111
	global_store_short v[150:151], v158, off
	global_store_short_d16_hi v[150:151], v158, off offset:32
	global_store_short v[150:151], v159, off offset:64
	global_store_short_d16_hi v[150:151], v159, off offset:96
	v_lshl_add_u64 v[150:151], v[150:151], 0, s[98:99]
	v_cvt_pk_bf16_f32 v156, v80, v84
	v_cvt_pk_bf16_f32 v157, v88, v92
	global_store_short v[150:151], v156, off
	global_store_short_d16_hi v[150:151], v156, off offset:32
	global_store_short v[150:151], v157, off offset:64
	global_store_short_d16_hi v[150:151], v157, off offset:96
	v_lshl_add_u64 v[150:151], v[150:151], 0, s[100:101]
	v_cvt_pk_bf16_f32 v158, v81, v85
	v_cvt_pk_bf16_f32 v159, v89, v93
	global_store_short v[150:151], v158, off
	global_store_short_d16_hi v[150:151], v158, off offset:32
	global_store_short v[150:151], v159, off offset:64
	global_store_short_d16_hi v[150:151], v159, off offset:96
	v_lshl_add_u64 v[150:151], v[150:151], 0, s[100:101]
	v_cvt_pk_bf16_f32 v156, v82, v86
	v_cvt_pk_bf16_f32 v157, v90, v94
	global_store_short v[150:151], v156, off
	global_store_short_d16_hi v[150:151], v156, off offset:32
	global_store_short v[150:151], v157, off offset:64
	global_store_short_d16_hi v[150:151], v157, off offset:96
	v_lshl_add_u64 v[150:151], v[150:151], 0, s[100:101]
	v_cvt_pk_bf16_f32 v158, v83, v87
	v_cvt_pk_bf16_f32 v159, v91, v95
	global_store_short v[150:151], v158, off
	global_store_short_d16_hi v[150:151], v158, off offset:32
	global_store_short v[150:151], v159, off offset:64
	global_store_short_d16_hi v[150:151], v159, off offset:96
	v_lshl_add_u64 v[150:151], v[150:151], 0, s[98:99]
	v_cvt_pk_bf16_f32 v156, v64, v68
	v_cvt_pk_bf16_f32 v157, v72, v76
	global_store_short v[150:151], v156, off
	global_store_short_d16_hi v[150:151], v156, off offset:32
	global_store_short v[150:151], v157, off offset:64
	global_store_short_d16_hi v[150:151], v157, off offset:96
	v_lshl_add_u64 v[150:151], v[150:151], 0, s[100:101]
	v_cvt_pk_bf16_f32 v158, v65, v69
	v_cvt_pk_bf16_f32 v159, v73, v77
	global_store_short v[150:151], v158, off
	global_store_short_d16_hi v[150:151], v158, off offset:32
	global_store_short v[150:151], v159, off offset:64
	global_store_short_d16_hi v[150:151], v159, off offset:96
	v_lshl_add_u64 v[150:151], v[150:151], 0, s[100:101]
	v_cvt_pk_bf16_f32 v156, v66, v70
	v_cvt_pk_bf16_f32 v157, v74, v78
	global_store_short v[150:151], v156, off
	global_store_short_d16_hi v[150:151], v156, off offset:32
	global_store_short v[150:151], v157, off offset:64
	global_store_short_d16_hi v[150:151], v157, off offset:96
	v_lshl_add_u64 v[150:151], v[150:151], 0, s[100:101]
	v_cvt_pk_bf16_f32 v158, v67, v71
	v_cvt_pk_bf16_f32 v159, v75, v79
	global_store_short v[150:151], v158, off
	global_store_short_d16_hi v[150:151], v158, off offset:32
	global_store_short v[150:151], v159, off offset:64
	global_store_short_d16_hi v[150:151], v159, off offset:96
	v_lshl_add_u64 v[150:151], v[150:151], 0, s[98:99]
	v_cvt_pk_bf16_f32 v156, v48, v52
	v_cvt_pk_bf16_f32 v157, v56, v60
	global_store_short v[150:151], v156, off
	global_store_short_d16_hi v[150:151], v156, off offset:32
	global_store_short v[150:151], v157, off offset:64
	global_store_short_d16_hi v[150:151], v157, off offset:96
	v_lshl_add_u64 v[150:151], v[150:151], 0, s[100:101]
	v_cvt_pk_bf16_f32 v158, v49, v53
	v_cvt_pk_bf16_f32 v159, v57, v61
	global_store_short v[150:151], v158, off
	global_store_short_d16_hi v[150:151], v158, off offset:32
	global_store_short v[150:151], v159, off offset:64
	global_store_short_d16_hi v[150:151], v159, off offset:96
	v_lshl_add_u64 v[150:151], v[150:151], 0, s[100:101]
	v_cvt_pk_bf16_f32 v156, v50, v54
	v_cvt_pk_bf16_f32 v157, v58, v62
	global_store_short v[150:151], v156, off
	global_store_short_d16_hi v[150:151], v156, off offset:32
	global_store_short v[150:151], v157, off offset:64
	global_store_short_d16_hi v[150:151], v157, off offset:96
	v_lshl_add_u64 v[150:151], v[150:151], 0, s[100:101]
	v_cvt_pk_bf16_f32 v158, v51, v55
	v_cvt_pk_bf16_f32 v159, v59, v63
	global_store_short v[150:151], v158, off
	global_store_short_d16_hi v[150:151], v158, off offset:32
	global_store_short v[150:151], v159, off offset:64
	global_store_short_d16_hi v[150:151], v159, off offset:96
	v_lshl_add_u64 v[150:151], v[150:151], 0, s[98:99]
	v_cvt_pk_bf16_f32 v156, v32, v36
	v_cvt_pk_bf16_f32 v157, v40, v44
	global_store_short v[150:151], v156, off
	global_store_short_d16_hi v[150:151], v156, off offset:32
	global_store_short v[150:151], v157, off offset:64
	global_store_short_d16_hi v[150:151], v157, off offset:96
	v_lshl_add_u64 v[150:151], v[150:151], 0, s[100:101]
	v_cvt_pk_bf16_f32 v158, v33, v37
	v_cvt_pk_bf16_f32 v159, v41, v45
	global_store_short v[150:151], v158, off
	global_store_short_d16_hi v[150:151], v158, off offset:32
	global_store_short v[150:151], v159, off offset:64
	global_store_short_d16_hi v[150:151], v159, off offset:96
	v_lshl_add_u64 v[150:151], v[150:151], 0, s[100:101]
	v_cvt_pk_bf16_f32 v156, v34, v38
	v_cvt_pk_bf16_f32 v157, v42, v46
	global_store_short v[150:151], v156, off
	global_store_short_d16_hi v[150:151], v156, off offset:32
	global_store_short v[150:151], v157, off offset:64
	global_store_short_d16_hi v[150:151], v157, off offset:96
	v_lshl_add_u64 v[150:151], v[150:151], 0, s[100:101]
	v_cvt_pk_bf16_f32 v158, v35, v39
	v_cvt_pk_bf16_f32 v159, v43, v47
	global_store_short v[150:151], v158, off
	global_store_short_d16_hi v[150:151], v158, off offset:32
	global_store_short v[150:151], v159, off offset:64
	global_store_short_d16_hi v[150:151], v159, off offset:96
	v_lshl_add_u64 v[150:151], v[150:151], 0, s[98:99]
	v_cvt_pk_bf16_f32 v156, v16, v20
	v_cvt_pk_bf16_f32 v157, v24, v28
	global_store_short v[150:151], v156, off
	global_store_short_d16_hi v[150:151], v156, off offset:32
	global_store_short v[150:151], v157, off offset:64
	global_store_short_d16_hi v[150:151], v157, off offset:96
	v_lshl_add_u64 v[150:151], v[150:151], 0, s[100:101]
	v_cvt_pk_bf16_f32 v158, v17, v21
	v_cvt_pk_bf16_f32 v159, v25, v29
	global_store_short v[150:151], v158, off
	global_store_short_d16_hi v[150:151], v158, off offset:32
	global_store_short v[150:151], v159, off offset:64
	global_store_short_d16_hi v[150:151], v159, off offset:96
	v_lshl_add_u64 v[150:151], v[150:151], 0, s[100:101]
	v_cvt_pk_bf16_f32 v156, v18, v22
	v_cvt_pk_bf16_f32 v157, v26, v30
	global_store_short v[150:151], v156, off
	global_store_short_d16_hi v[150:151], v156, off offset:32
	global_store_short v[150:151], v157, off offset:64
	global_store_short_d16_hi v[150:151], v157, off offset:96
	v_lshl_add_u64 v[150:151], v[150:151], 0, s[100:101]
	v_cvt_pk_bf16_f32 v158, v19, v23
	v_cvt_pk_bf16_f32 v159, v27, v31
	global_store_short v[150:151], v158, off
	global_store_short_d16_hi v[150:151], v158, off offset:32
	global_store_short v[150:151], v159, off offset:64
	global_store_short_d16_hi v[150:151], v159, off offset:96
	v_lshl_add_u64 v[150:151], v[150:151], 0, s[98:99]
	v_cvt_pk_bf16_f32 v156, v0, v4
	v_cvt_pk_bf16_f32 v157, v8, v12
	global_store_short v[150:151], v156, off
	global_store_short_d16_hi v[150:151], v156, off offset:32
	global_store_short v[150:151], v157, off offset:64
	global_store_short_d16_hi v[150:151], v157, off offset:96
	v_lshl_add_u64 v[150:151], v[150:151], 0, s[100:101]
	v_cvt_pk_bf16_f32 v158, v1, v5
	v_cvt_pk_bf16_f32 v159, v9, v13
	global_store_short v[150:151], v158, off
	global_store_short_d16_hi v[150:151], v158, off offset:32
	global_store_short v[150:151], v159, off offset:64
	global_store_short_d16_hi v[150:151], v159, off offset:96
	v_lshl_add_u64 v[150:151], v[150:151], 0, s[100:101]
	v_cvt_pk_bf16_f32 v156, v2, v6
	v_cvt_pk_bf16_f32 v157, v10, v14
	global_store_short v[150:151], v156, off
	global_store_short_d16_hi v[150:151], v156, off offset:32
	global_store_short v[150:151], v157, off offset:64
	global_store_short_d16_hi v[150:151], v157, off offset:96
	v_lshl_add_u64 v[150:151], v[150:151], 0, s[100:101]
	v_cvt_pk_bf16_f32 v158, v3, v7
	v_cvt_pk_bf16_f32 v159, v11, v15
	global_store_short v[150:151], v158, off
	global_store_short_d16_hi v[150:151], v158, off offset:32
	global_store_short v[150:151], v159, off offset:64
	global_store_short_d16_hi v[150:151], v159, off offset:96
	s_branch .Lepi1_0_join
.Lepi1_0_slow:
	v_ashrrev_i32_e32 v139, 31, v138
	v_or_b32_e32 v152, v138, v128
	v_mad_i64_i32 v[140:141], s[0:1], v153, s43, v[140:141]
	v_lshl_add_u64 v[140:141], v[138:139], 1, v[140:141]
	v_lshl_add_u64 v[140:141], v[140:141], 0, v[130:131]
	v_cmp_gt_i32_e32 vcc, s44, v152
	s_and_saveexec_b64 s[0:1], vcc
	s_cbranch_execz .LBB0_209
	v_bfe_u32 v153, v112, 16, 1
	v_add3_u32 v153, v112, v153, s45
	global_store_short_d16_hi v[140:141], v153, off

.Lepi1_1_join:
	s_add_i32 s2, s2, s3
	s_add_i32 s25, s25, s26
	s_xor_b64 s[12:13], s[12:13], s[14:15]
	s_cmpk_gt_i32 s2, 0xdb
	s_cbranch_scc1 .LBB0_1953

.LBB0_1692:
	s_mul_i32 s8, s6, 0x6000
	s_waitcnt vmcnt(6)
	s_add_i32 s10, s23, s8
	s_mul_i32 s98, s7, 0x6000
	v_lshl_add_u64 v[186:187], v[142:143], 0, s[0:1]
	v_lshl_add_u64 v[204:205], v[140:141], 0, s[0:1]
	s_add_i32 s99, s10, s24
	s_waitcnt lgkmcnt(0)
	s_barrier
	v_add_u32_e32 v184, s98, v144
	v_add_u32_e32 v185, s98, v146
	ds_read_b128 v[168:171], v185
	ds_read_b128 v[152:155], v184
	ds_read_b128 v[172:175], v185 offset:1024
	ds_read_b128 v[176:179], v185 offset:2048
	ds_read_b128 v[180:183], v185 offset:3072
	ds_read_b128 v[156:159], v184 offset:1024
	ds_read_b128 v[160:163], v184 offset:2048
	ds_read_b128 v[164:167], v184 offset:3072
	ds_read_b128 v[188:191], v184 offset:4096
	ds_read_b128 v[192:195], v184 offset:5120
	ds_read_b128 v[196:199], v184 offset:6144
	ds_read_b128 v[200:203], v184 offset:7168
	s_mov_b64 s[100:101], 0x80
	v_lshl_add_u64 v[206:207], v[186:187], 0, s[100:101]
	s_mov_b32 m0, s10
	s_waitcnt lgkmcnt(10)
	v_mfma_f32_16x16x32_bf16 v[84:87], v[152:155], v[168:171], v[84:87]
	global_load_lds_dwordx4 v[206:207], off
	s_waitcnt lgkmcnt(9)
	v_mfma_f32_16x16x32_bf16 v[76:79], v[152:155], v[172:175], v[76:79]
	s_mov_b64 s[100:101], 0x8080
	v_lshl_add_u64 v[206:207], v[186:187], 0, s[100:101]
	s_add_i32 m0, s10, 0x400
	s_waitcnt lgkmcnt(8)
	v_mfma_f32_16x16x32_bf16 v[68:71], v[152:155], v[176:179], v[68:71]
	global_load_lds_dwordx4 v[206:207], off
	s_waitcnt lgkmcnt(7)
	v_mfma_f32_16x16x32_bf16 v[60:63], v[152:155], v[180:183], v[60:63]
	s_mov_b64 s[100:101], 0x10080
	v_lshl_add_u64 v[206:207], v[186:187], 0, s[100:101]
	s_add_i32 m0, s10, 0x800
	s_waitcnt lgkmcnt(6)
	v_mfma_f32_16x16x32_bf16 v[52:55], v[156:159], v[168:171], v[52:55]
	global_load_lds_dwordx4 v[206:207], off
	v_mfma_f32_16x16x32_bf16 v[44:47], v[156:159], v[172:175], v[44:47]
	v_mfma_f32_16x16x32_bf16 v[36:39], v[156:159], v[176:179], v[36:39]
	s_mov_b64 s[100:101], 0x18080
	v_lshl_add_u64 v[206:207], v[186:187], 0, s[100:101]
	s_add_i32 m0, s10, 0xc00
	v_mfma_f32_16x16x32_bf16 v[32:35], v[156:159], v[180:183], v[32:35]
	global_load_lds_dwordx4 v[206:207], off
	s_waitcnt lgkmcnt(5)
	v_mfma_f32_16x16x32_bf16 v[28:31], v[160:163], v[168:171], v[28:31]
	s_mov_b64 s[100:101], 0x580080
	v_lshl_add_u64 v[206:207], v[204:205], 0, s[100:101]
	s_add_i32 m0, s99, 0x4000
	v_mfma_f32_16x16x32_bf16 v[24:27], v[160:163], v[172:175], v[24:27]
	global_load_lds_dwordx4 v[206:207], off
	v_mfma_f32_16x16x32_bf16 v[20:23], v[160:163], v[176:179], v[20:23]
	s_mov_b64 s[100:101], 0x588080
	v_lshl_add_u64 v[206:207], v[204:205], 0, s[100:101]
	s_add_i32 m0, s99, 0x4400
	v_mfma_f32_16x16x32_bf16 v[16:19], v[160:163], v[180:183], v[16:19]
	global_load_lds_dwordx4 v[206:207], off
	s_waitcnt lgkmcnt(4)
	v_mfma_f32_16x16x32_bf16 v[12:15], v[164:167], v[168:171], v[12:15]
	v_mfma_f32_16x16x32_bf16 v[8:11], v[164:167], v[172:175], v[8:11]
	v_mfma_f32_16x16x32_bf16 v[4:7], v[164:167], v[176:179], v[4:7]
	v_mfma_f32_16x16x32_bf16 v[0:3], v[164:167], v[180:183], v[0:3]
	s_waitcnt lgkmcnt(3)
	v_mfma_f32_16x16x32_bf16 v[124:127], v[188:191], v[168:171], v[124:127]
	v_mfma_f32_16x16x32_bf16 v[120:123], v[188:191], v[172:175], v[120:123]
	v_mfma_f32_16x16x32_bf16 v[116:119], v[188:191], v[176:179], v[116:119]
	v_mfma_f32_16x16x32_bf16 v[112:115], v[188:191], v[180:183], v[112:115]
	s_waitcnt lgkmcnt(2)
	v_mfma_f32_16x16x32_bf16 v[108:111], v[192:195], v[168:171], v[108:111]
	v_mfma_f32_16x16x32_bf16 v[104:107], v[192:195], v[172:175], v[104:107]
	v_mfma_f32_16x16x32_bf16 v[100:103], v[192:195], v[176:179], v[100:103]
	v_mfma_f32_16x16x32_bf16 v[96:99], v[192:195], v[180:183], v[96:99]
	s_waitcnt lgkmcnt(1)
	v_mfma_f32_16x16x32_bf16 v[92:95], v[196:199], v[168:171], v[92:95]
	v_mfma_f32_16x16x32_bf16 v[88:91], v[196:199], v[172:175], v[88:91]
	v_mfma_f32_16x16x32_bf16 v[80:83], v[196:199], v[176:179], v[80:83]
	v_mfma_f32_16x16x32_bf16 v[72:75], v[196:199], v[180:183], v[72:75]
	s_waitcnt lgkmcnt(0)
	v_mfma_f32_16x16x32_bf16 v[64:67], v[200:203], v[168:171], v[64:67]
	v_mfma_f32_16x16x32_bf16 v[56:59], v[200:203], v[172:175], v[56:59]
	v_mfma_f32_16x16x32_bf16 v[48:51], v[200:203], v[176:179], v[48:51]
	v_mfma_f32_16x16x32_bf16 v[40:43], v[200:203], v[180:183], v[40:43]
	s_add_i32 s8, s7, 1
	s_cmp_lg_u32 s7, 2
	s_cselect_b32 s7, s8, 0
	s_add_i32 s8, s6, 1
	s_cmp_lg_u32 s6, 2
	s_cselect_b32 s6, s8, 0
	s_add_u32 s0, s0, 64
	s_addc_u32 s1, s1, 0
	s_cmpk_eq_i32 s0, 0x780
	s_cbranch_scc0 .LBB0_1692
	s_waitcnt vmcnt(6)
	s_waitcnt lgkmcnt(0)
	s_barrier
	ds_read_b128 v[140:143], v144
	ds_read_b128 v[152:155], v144 offset:1024
	ds_read_b128 v[156:159], v144 offset:2048
	ds_read_b128 v[160:163], v144 offset:3072
	ds_read_b128 v[164:167], v146
	ds_read_b128 v[168:171], v146 offset:1024
	ds_read_b128 v[172:175], v146 offset:2048
	ds_read_b128 v[176:179], v146 offset:3072
	s_waitcnt lgkmcnt(0)
	s_nop 0
	v_mfma_f32_16x16x32_bf16 v[84:87], v[140:143], v[164:167], v[84:87]
	v_mfma_f32_16x16x32_bf16 v[76:79], v[140:143], v[168:171], v[76:79]
	v_mfma_f32_16x16x32_bf16 v[68:71], v[140:143], v[172:175], v[68:71]
	v_mfma_f32_16x16x32_bf16 v[60:63], v[140:143], v[176:179], v[60:63]
	v_mfma_f32_16x16x32_bf16 v[52:55], v[152:155], v[164:167], v[52:55]
	v_mfma_f32_16x16x32_bf16 v[44:47], v[152:155], v[168:171], v[44:47]
	v_mfma_f32_16x16x32_bf16 v[36:39], v[152:155], v[172:175], v[36:39]
	v_mfma_f32_16x16x32_bf16 v[32:35], v[152:155], v[176:179], v[32:35]
	v_mfma_f32_16x16x32_bf16 v[28:31], v[156:159], v[164:167], v[28:31]
	v_mfma_f32_16x16x32_bf16 v[24:27], v[156:159], v[168:171], v[24:27]
	v_mfma_f32_16x16x32_bf16 v[20:23], v[156:159], v[172:175], v[20:23]
	v_mfma_f32_16x16x32_bf16 v[16:19], v[156:159], v[176:179], v[16:19]
	v_mfma_f32_16x16x32_bf16 v[12:15], v[160:163], v[164:167], v[12:15]
	v_mfma_f32_16x16x32_bf16 v[8:11], v[160:163], v[168:171], v[8:11]
	v_mfma_f32_16x16x32_bf16 v[4:7], v[160:163], v[172:175], v[4:7]
	v_mfma_f32_16x16x32_bf16 v[0:3], v[160:163], v[176:179], v[0:3]
	ds_read_b128 v[140:143], v144 offset:4096
	ds_read_b128 v[152:155], v144 offset:5120
	ds_read_b128 v[156:159], v144 offset:6144
	ds_read_b128 v[160:163], v144 offset:7168
	s_waitcnt lgkmcnt(0)
	s_nop 0
	v_mfma_f32_16x16x32_bf16 v[180:183], v[140:143], v[164:167], v[124:127]
	v_mfma_f32_16x16x32_bf16 v[184:187], v[140:143], v[168:171], v[120:123]
	v_mfma_f32_16x16x32_bf16 v[188:191], v[140:143], v[172:175], v[116:119]
	v_mfma_f32_16x16x32_bf16 v[140:143], v[140:143], v[176:179], v[112:115]
	v_mfma_f32_16x16x32_bf16 v[192:195], v[152:155], v[164:167], v[108:111]
	v_mfma_f32_16x16x32_bf16 v[196:199], v[152:155], v[168:171], v[104:107]
	v_mfma_f32_16x16x32_bf16 v[200:203], v[152:155], v[172:175], v[100:103]
	v_mfma_f32_16x16x32_bf16 v[152:155], v[152:155], v[176:179], v[96:99]
	v_mfma_f32_16x16x32_bf16 v[204:207], v[156:159], v[164:167], v[92:95]
	v_mfma_f32_16x16x32_bf16 v[208:211], v[156:159], v[168:171], v[88:91]
	v_mfma_f32_16x16x32_bf16 v[212:215], v[156:159], v[172:175], v[80:83]
	v_mfma_f32_16x16x32_bf16 v[156:159], v[156:159], v[176:179], v[72:75]
	v_mfma_f32_16x16x32_bf16 v[164:167], v[160:163], v[164:167], v[64:67]
	v_mfma_f32_16x16x32_bf16 v[168:171], v[160:163], v[168:171], v[56:59]
	v_mfma_f32_16x16x32_bf16 v[172:175], v[160:163], v[172:175], v[48:51]
	v_mfma_f32_16x16x32_bf16 v[160:163], v[160:163], v[176:179], v[40:43]
	s_waitcnt vmcnt(0)
	s_waitcnt lgkmcnt(0)
	s_barrier
	ds_read_b128 v[40:43], v150
	ds_read_b128 v[48:51], v150 offset:1024
	ds_read_b128 v[56:59], v150 offset:2048
	ds_read_b128 v[176:179], v150 offset:3072
	ds_read_b128 v[216:219], v151
	ds_read_b128 v[220:223], v151 offset:1024
	ds_read_b128 v[228:231], v151 offset:2048
	ds_read_b128 v[232:235], v151 offset:3072
	s_waitcnt lgkmcnt(0)
	s_nop 0
	v_mfma_f32_16x16x32_bf16 v[116:119], v[40:43], v[220:223], v[76:79]
	v_mfma_f32_16x16x32_bf16 v[120:123], v[40:43], v[228:231], v[68:71]
	v_mfma_f32_16x16x32_bf16 v[64:67], v[176:179], v[216:219], v[12:15]
	v_mfma_f32_16x16x32_bf16 v[68:71], v[176:179], v[220:223], v[8:11]
	v_mfma_f32_16x16x32_bf16 v[72:75], v[176:179], v[228:231], v[4:7]
	v_mfma_f32_16x16x32_bf16 v[76:79], v[176:179], v[232:235], v[0:3]
	ds_read_b128 v[0:3], v150 offset:4096
	ds_read_b128 v[4:7], v150 offset:5120
	ds_read_b128 v[8:11], v150 offset:6144
	ds_read_b128 v[12:15], v150 offset:7168
	s_waitcnt lgkmcnt(0)
	v_mfma_f32_16x16x32_bf16 v[112:115], v[40:43], v[216:219], v[84:87]
	v_mfma_f32_16x16x32_bf16 v[124:127], v[40:43], v[232:235], v[60:63]
	v_mfma_f32_16x16x32_bf16 v[96:99], v[48:51], v[216:219], v[52:55]
	v_mfma_f32_16x16x32_bf16 v[100:103], v[48:51], v[220:223], v[44:47]
	v_mfma_f32_16x16x32_bf16 v[104:107], v[48:51], v[228:231], v[36:39]
	v_mfma_f32_16x16x32_bf16 v[108:111], v[48:51], v[232:235], v[32:35]
	v_mfma_f32_16x16x32_bf16 v[80:83], v[56:59], v[216:219], v[28:31]
	v_mfma_f32_16x16x32_bf16 v[84:87], v[56:59], v[220:223], v[24:27]
	v_mfma_f32_16x16x32_bf16 v[88:91], v[56:59], v[228:231], v[20:23]
	v_mfma_f32_16x16x32_bf16 v[92:95], v[56:59], v[232:235], v[16:19]
	v_mfma_f32_16x16x32_bf16 v[48:51], v[0:3], v[216:219], v[180:183]
	v_mfma_f32_16x16x32_bf16 v[52:55], v[0:3], v[220:223], v[184:187]
	v_mfma_f32_16x16x32_bf16 v[56:59], v[0:3], v[228:231], v[188:191]
	v_mfma_f32_16x16x32_bf16 v[60:63], v[0:3], v[232:235], v[140:143]
	v_mfma_f32_16x16x32_bf16 v[32:35], v[4:7], v[216:219], v[192:195]
	v_mfma_f32_16x16x32_bf16 v[36:39], v[4:7], v[220:223], v[196:199]
	v_mfma_f32_16x16x32_bf16 v[40:43], v[4:7], v[228:231], v[200:203]
	v_mfma_f32_16x16x32_bf16 v[44:47], v[4:7], v[232:235], v[152:155]
	v_mfma_f32_16x16x32_bf16 v[16:19], v[8:11], v[216:219], v[204:207]
	v_mfma_f32_16x16x32_bf16 v[20:23], v[8:11], v[220:223], v[208:211]
	v_mfma_f32_16x16x32_bf16 v[24:27], v[8:11], v[228:231], v[212:215]
	v_mfma_f32_16x16x32_bf16 v[28:31], v[8:11], v[232:235], v[156:159]
	v_mfma_f32_16x16x32_bf16 v[0:3], v[12:15], v[216:219], v[164:167]
	v_mfma_f32_16x16x32_bf16 v[4:7], v[12:15], v[220:223], v[168:171]
	v_mfma_f32_16x16x32_bf16 v[8:11], v[12:15], v[228:231], v[172:175]
	v_mfma_f32_16x16x32_bf16 v[12:15], v[12:15], v[232:235], v[160:163]
	v_add_u32_e32 v152, s4, v129
	v_or_b32_e32 v153, v152, v149
	v_or_b32_e32 v140, s5, v145
	v_mov_b32_e32 v155, v153
	v_mov_b64_e32 v[142:143], s[94:95]
	s_waitcnt lgkmcnt(0)
	s_barrier
	s_cmp_gt_u32 s5, 0xa00
	s_cbranch_scc1 .Lepi1_1_slow
	s_cmp_lt_u32 s4, 0x1000
	s_cbranch_scc0 .Lepi1_1_fast
	s_cmp_eq_u32 s5, 0x180
	s_cbranch_scc1 .Lepi1_1_slow
	s_cmp_eq_u32 s5, 0x200
	s_cbranch_scc1 .Lepi1_1_slow
.Lepi1_1_fast:
	v_add_u32_e32 v156, s4, v129
	v_or_b32_e32 v156, v156, v149
	v_or_b32_e32 v154, s5, v145
	v_mov_b32_e32 v155, 0
	v_mov_b64_e32 v[152:153], s[94:95]
	v_mad_i64_i32 v[152:153], vcc, v156, s39, v[152:153]
	v_lshl_add_u64 v[152:153], v[154:155], 1, v[152:153]
	v_lshl_add_u64 v[152:153], v[152:153], 0, v[130:131]
	s_mov_b64 s[100:101], 0x1520
	s_mov_b64 s[98:99], 0x112a0
	v_cvt_pk_bf16_f32 v158, v112, v116
	v_cvt_pk_bf16_f32 v159, v120, v124
	global_store_short v[152:153], v158, off
	global_store_short_d16_hi v[152:153], v158, off offset:32
	global_store_short v[152:153], v159, off offset:64
	global_store_short_d16_hi v[152:153], v159, off offset:96
	v_lshl_add_u64 v[152:153], v[152:153], 0, s[100:101]
	v_cvt_pk_bf16_f32 v160, v113, v117
	v_cvt_pk_bf16_f32 v161, v121, v125
	global_store_short v[152:153], v160, off
	global_store_short_d16_hi v[152:153], v160, off offset:32
	global_store_short v[152:153], v161, off offset:64
	global_store_short_d16_hi v[152:153], v161, off offset:96
	v_lshl_add_u64 v[152:153], v[152:153], 0, s[100:101]
	v_cvt_pk_bf16_f32 v158, v114, v118
	v_cvt_pk_bf16_f32 v159, v122, v126
	global_store_short v[152:153], v158, off
	global_store_short_d16_hi v[152:153], v158, off offset:32
	global_store_short v[152:153], v159, off offset:64
	global_store_short_d16_hi v[152:153], v159, off offset:96
	v_lshl_add_u64 v[152:153], v[152:153], 0, s[100:101]
	v_cvt_pk_bf16_f32 v160, v115, v119
	v_cvt_pk_bf16_f32 v161, v123, v127
	global_store_short v[152:153], v160, off
	global_store_short_d16_hi v[152:153], v160, off offset:32
	global_store_short v[152:153], v161, off offset:64
	global_store_short_d16_hi v[152:153], v161, off offset:96
	v_lshl_add_u64 v[152:153], v[152:153], 0, s[98:99]
	v_cvt_pk_bf16_f32 v158, v96, v100
	v_cvt_pk_bf16_f32 v159, v104, v108
	global_store_short v[152:153], v158, off
	global_store_short_d16_hi v[152:153], v158, off offset:32
	global_store_short v[152:153], v159, off offset:64
	global_store_short_d16_hi v[152:153], v159, off offset:96
	v_lshl_add_u64 v[152:153], v[152:153], 0, s[100:101]
	v_cvt_pk_bf16_f32 v160, v97, v101
	v_cvt_pk_bf16_f32 v161, v105, v109
	global_store_short v[152:153], v160, off
	global_store_short_d16_hi v[152:153], v160, off offset:32
	global_store_short v[152:153], v161, off offset:64
	global_store_short_d16_hi v[152:153], v161, off offset:96
	v_lshl_add_u64 v[152:153], v[152:153], 0, s[100:101]
	v_cvt_pk_bf16_f32 v158, v98, v102
	v_cvt_pk_bf16_f32 v159, v106, v110
	global_store_short v[152:153], v158, off
	global_store_short_d16_hi v[152:153], v158, off offset:32
	global_store_short v[152:153], v159, off offset:64
	global_store_short_d16_hi v[152:153], v159, off offset:96
	v_lshl_add_u64 v[152:153], v[152:153], 0, s[100:101]
	v_cvt_pk_bf16_f32 v160, v99, v103
	v_cvt_pk_bf16_f32 v161, v107, v111
	global_store_short v[152:153], v160, off
	global_store_short_d16_hi v[152:153], v160, off offset:32
	global_store_short v[152:153], v161, off offset:64
	global_store_short_d16_hi v[152:153], v161, off offset:96
	v_lshl_add_u64 v[152:153], v[152:153], 0, s[98:99]
	v_cvt_pk_bf16_f32 v158, v80, v84
	v_cvt_pk_bf16_f32 v159, v88, v92
	global_store_short v[152:153], v158, off
	global_store_short_d16_hi v[152:153], v158, off offset:32
	global_store_short v[152:153], v159, off offset:64
	global_store_short_d16_hi v[152:153], v159, off offset:96
	v_lshl_add_u64 v[152:153], v[152:153], 0, s[100:101]
	v_cvt_pk_bf16_f32 v160, v81, v85
	v_cvt_pk_bf16_f32 v161, v89, v93
	global_store_short v[152:153], v160, off
	global_store_short_d16_hi v[152:153], v160, off offset:32
	global_store_short v[152:153], v161, off offset:64
	global_store_short_d16_hi v[152:153], v161, off offset:96
	v_lshl_add_u64 v[152:153], v[152:153], 0, s[100:101]
	v_cvt_pk_bf16_f32 v158, v82, v86
	v_cvt_pk_bf16_f32 v159, v90, v94
	global_store_short v[152:153], v158, off
	global_store_short_d16_hi v[152:153], v158, off offset:32
	global_store_short v[152:153], v159, off offset:64
	global_store_short_d16_hi v[152:153], v159, off offset:96
	v_lshl_add_u64 v[152:153], v[152:153], 0, s[100:101]
	v_cvt_pk_bf16_f32 v160, v83, v87
	v_cvt_pk_bf16_f32 v161, v91, v95
	global_store_short v[152:153], v160, off
	global_store_short_d16_hi v[152:153], v160, off offset:32
	global_store_short v[152:153], v161, off offset:64
	global_store_short_d16_hi v[152:153], v161, off offset:96
	v_lshl_add_u64 v[152:153], v[152:153], 0, s[98:99]
	v_cvt_pk_bf16_f32 v158, v64, v68
	v_cvt_pk_bf16_f32 v159, v72, v76
	global_store_short v[152:153], v158, off
	global_store_short_d16_hi v[152:153], v158, off offset:32
	global_store_short v[152:153], v159, off offset:64
	global_store_short_d16_hi v[152:153], v159, off offset:96
	v_lshl_add_u64 v[152:153], v[152:153], 0, s[100:101]
	v_cvt_pk_bf16_f32 v160, v65, v69
	v_cvt_pk_bf16_f32 v161, v73, v77
	global_store_short v[152:153], v160, off
	global_store_short_d16_hi v[152:153], v160, off offset:32
	global_store_short v[152:153], v161, off offset:64
	global_store_short_d16_hi v[152:153], v161, off offset:96
	v_lshl_add_u64 v[152:153], v[152:153], 0, s[100:101]
	v_cvt_pk_bf16_f32 v158, v66, v70
	v_cvt_pk_bf16_f32 v159, v74, v78
	global_store_short v[152:153], v158, off
	global_store_short_d16_hi v[152:153], v158, off offset:32
	global_store_short v[152:153], v159, off offset:64
	global_store_short_d16_hi v[152:153], v159, off offset:96
	v_lshl_add_u64 v[152:153], v[152:153], 0, s[100:101]
	v_cvt_pk_bf16_f32 v160, v67, v71
	v_cvt_pk_bf16_f32 v161, v75, v79
	global_store_short v[152:153], v160, off
	global_store_short_d16_hi v[152:153], v160, off offset:32
	global_store_short v[152:153], v161, off offset:64
	global_store_short_d16_hi v[152:153], v161, off offset:96
	v_lshl_add_u64 v[152:153], v[152:153], 0, s[98:99]
	v_cvt_pk_bf16_f32 v158, v48, v52
	v_cvt_pk_bf16_f32 v159, v56, v60
	global_store_short v[152:153], v158, off
	global_store_short_d16_hi v[152:153], v158, off offset:32
	global_store_short v[152:153], v159, off offset:64
	global_store_short_d16_hi v[152:153], v159, off offset:96
	v_lshl_add_u64 v[152:153], v[152:153], 0, s[100:101]
	v_cvt_pk_bf16_f32 v160, v49, v53
	v_cvt_pk_bf16_f32 v161, v57, v61
	global_store_short v[152:153], v160, off
	global_store_short_d16_hi v[152:153], v160, off offset:32
	global_store_short v[152:153], v161, off offset:64
	global_store_short_d16_hi v[152:153], v161, off offset:96
	v_lshl_add_u64 v[152:153], v[152:153], 0, s[100:101]
	v_cvt_pk_bf16_f32 v158, v50, v54
	v_cvt_pk_bf16_f32 v159, v58, v62
	global_store_short v[152:153], v158, off
	global_store_short_d16_hi v[152:153], v158, off offset:32
	global_store_short v[152:153], v159, off offset:64
	global_store_short_d16_hi v[152:153], v159, off offset:96
	v_lshl_add_u64 v[152:153], v[152:153], 0, s[100:101]
	v_cvt_pk_bf16_f32 v160, v51, v55
	v_cvt_pk_bf16_f32 v161, v59, v63
	global_store_short v[152:153], v160, off
	global_store_short_d16_hi v[152:153], v160, off offset:32
	global_store_short v[152:153], v161, off offset:64
	global_store_short_d16_hi v[152:153], v161, off offset:96
	v_lshl_add_u64 v[152:153], v[152:153], 0, s[98:99]
	v_cvt_pk_bf16_f32 v158, v32, v36
	v_cvt_pk_bf16_f32 v159, v40, v44
	global_store_short v[152:153], v158, off
	global_store_short_d16_hi v[152:153], v158, off offset:32
	global_store_short v[152:153], v159, off offset:64
	global_store_short_d16_hi v[152:153], v159, off offset:96
	v_lshl_add_u64 v[152:153], v[152:153], 0, s[100:101]
	v_cvt_pk_bf16_f32 v160, v33, v37
	v_cvt_pk_bf16_f32 v161, v41, v45
	global_store_short v[152:153], v160, off
	global_store_short_d16_hi v[152:153], v160, off offset:32
	global_store_short v[152:153], v161, off offset:64
	global_store_short_d16_hi v[152:153], v161, off offset:96
	v_lshl_add_u64 v[152:153], v[152:153], 0, s[100:101]
	v_cvt_pk_bf16_f32 v158, v34, v38
	v_cvt_pk_bf16_f32 v159, v42, v46
	global_store_short v[152:153], v158, off
	global_store_short_d16_hi v[152:153], v158, off offset:32
	global_store_short v[152:153], v159, off offset:64
	global_store_short_d16_hi v[152:153], v159, off offset:96
	v_lshl_add_u64 v[152:153], v[152:153], 0, s[100:101]
	v_cvt_pk_bf16_f32 v160, v35, v39
	v_cvt_pk_bf16_f32 v161, v43, v47
	global_store_short v[152:153], v160, off
	global_store_short_d16_hi v[152:153], v160, off offset:32
	global_store_short v[152:153], v161, off offset:64
	global_store_short_d16_hi v[152:153], v161, off offset:96
	v_lshl_add_u64 v[152:153], v[152:153], 0, s[98:99]
	v_cvt_pk_bf16_f32 v158, v16, v20
	v_cvt_pk_bf16_f32 v159, v24, v28
	global_store_short v[152:153], v158, off
	global_store_short_d16_hi v[152:153], v158, off offset:32
	global_store_short v[152:153], v159, off offset:64
	global_store_short_d16_hi v[152:153], v159, off offset:96
	v_lshl_add_u64 v[152:153], v[152:153], 0, s[100:101]
	v_cvt_pk_bf16_f32 v160, v17, v21
	v_cvt_pk_bf16_f32 v161, v25, v29
	global_store_short v[152:153], v160, off
	global_store_short_d16_hi v[152:153], v160, off offset:32
	global_store_short v[152:153], v161, off offset:64
	global_store_short_d16_hi v[152:153], v161, off offset:96
	v_lshl_add_u64 v[152:153], v[152:153], 0, s[100:101]
	v_cvt_pk_bf16_f32 v158, v18, v22
	v_cvt_pk_bf16_f32 v159, v26, v30
	global_store_short v[152:153], v158, off
	global_store_short_d16_hi v[152:153], v158, off offset:32
	global_store_short v[152:153], v159, off offset:64
	global_store_short_d16_hi v[152:153], v159, off offset:96
	v_lshl_add_u64 v[152:153], v[152:153], 0, s[100:101]
	v_cvt_pk_bf16_f32 v160, v19, v23
	v_cvt_pk_bf16_f32 v161, v27, v31
	global_store_short v[152:153], v160, off
	global_store_short_d16_hi v[152:153], v160, off offset:32
	global_store_short v[152:153], v161, off offset:64
	global_store_short_d16_hi v[152:153], v161, off offset:96
	v_lshl_add_u64 v[152:153], v[152:153], 0, s[98:99]
	v_cvt_pk_bf16_f32 v158, v0, v4
	v_cvt_pk_bf16_f32 v159, v8, v12
	global_store_short v[152:153], v158, off
	global_store_short_d16_hi v[152:153], v158, off offset:32
	global_store_short v[152:153], v159, off offset:64
	global_store_short_d16_hi v[152:153], v159, off offset:96
	v_lshl_add_u64 v[152:153], v[152:153], 0, s[100:101]
	v_cvt_pk_bf16_f32 v160, v1, v5
	v_cvt_pk_bf16_f32 v161, v9, v13
	global_store_short v[152:153], v160, off
	global_store_short_d16_hi v[152:153], v160, off offset:32
	global_store_short v[152:153], v161, off offset:64
	global_store_short_d16_hi v[152:153], v161, off offset:96
	v_lshl_add_u64 v[152:153], v[152:153], 0, s[100:101]
	v_cvt_pk_bf16_f32 v158, v2, v6
	v_cvt_pk_bf16_f32 v159, v10, v14
	global_store_short v[152:153], v158, off
	global_store_short_d16_hi v[152:153], v158, off offset:32
	global_store_short v[152:153], v159, off offset:64
	global_store_short_d16_hi v[152:153], v159, off offset:96
	v_lshl_add_u64 v[152:153], v[152:153], 0, s[100:101]
	v_cvt_pk_bf16_f32 v160, v3, v7
	v_cvt_pk_bf16_f32 v161, v11, v15
	global_store_short v[152:153], v160, off
	global_store_short_d16_hi v[152:153], v160, off offset:32
	global_store_short v[152:153], v161, off offset:64
	global_store_short_d16_hi v[152:153], v161, off offset:96
	s_branch .Lepi1_1_join
.Lepi1_1_slow:
	v_ashrrev_i32_e32 v141, 31, v140
	v_or_b32_e32 v154, v140, v128
	v_mad_i64_i32 v[142:143], s[0:1], v155, s39, v[142:143]
	v_lshl_add_u64 v[142:143], v[140:141], 1, v[142:143]
	v_lshl_add_u64 v[142:143], v[142:143], 0, v[130:131]
	v_cmp_gt_i32_e32 vcc, s40, v154
	s_and_saveexec_b64 s[0:1], vcc
	s_cbranch_execz .LBB0_1695
	v_bfe_u32 v155, v112, 16, 1
	v_add3_u32 v155, v112, v155, s41
	global_store_short_d16_hi v[142:143], v155, off
